# ph3 reorder selects odd blocks (parity) instead of blocks>=256 to start with attention
# baseline (speedup 1.0000x reference)
; #define KARGP(z_) ((const P*)(const void*)((const __attribute__((address_space(4))) char*)__builtin_amdgcn_kernarg_segment_ptr() + (z_)))
; __global__ void __launch_bounds__(NTHR, 2) mega(P p) {
;     ...
;     switch (ph) {
;       case -1: {
;         OPAQUE_Z; const P& q = *KARGP(zz);
;         ph_fold(q, smem);
;         ph_xinit(q);
;         break;
;       }
;       case 0: {
;         OPAQUE_Z; const P& q = *KARGP(zz);
;         gemm_phase<EPI_BF16>(q, l, (const u16*)(q.ws + O_XMOD), 1024, (const u16*)(q.ws + O_WINT) + (size_t)l * 3072 * 1024, 1024, 1024,
;                              T_ALL / 128, 24, (void*)(q.ws + O_P), LDP, smem);
;         break;
;       }
;       case 1: {
;         OPAQUE_Z; const P& q = *KARGP(zz);
;         gemm_phase<EPI_Q>(q, l, (const u16*)(q.ws + O_P), LDP, (const u16*)(q.ws + O_WUQT) + (size_t)l * 384 * 256, 256, 256,
;                           T_ALL / 128, 3, nullptr, 0, smem);
;         gemm_phase<EPI_KV>(q, l, (const u16*)(q.ws + O_P) + 256, LDP, (const u16*)(q.ws + O_WUKVT) + (size_t)l * 512 * 128, 128, 128,
;                            T_ALL / 128, 4, nullptr, 0, smem, (int)gridDim.x - (int)((T_ALL / 128 * 3) % gridDim.x));
;         ph_prep(q, l, smem);
;         break;
;       }
;       case 2: {
;         OPAQUE_Z; const P& q = *KARGP(zz);
;         ph_scan1(q, smem);
;         break;
;       }
;       case 3: {
;         OPAQUE_Z; const P& q = *KARGP(zz);
;         ph_scan2(q);
;         ph_attn(q, need_ctx, smem);
.LBB0_1225:
	v_readlane_b32 s2, v254, 22
	s_cmp_gt_i32 s2, 0
	s_mov_b64 s[2:3], -1
	s_cbranch_scc0 .LBB0_1453
	v_readlane_b32 s0, v254, 22
	s_cmp_lt_i32 s0, 2
	s_mov_b64 s[0:1], -1
	s_cbranch_scc1 .LBB0_1371
	v_readlane_b32 s0, v254, 22
	s_cmp_gt_i32 s0, 2
	s_mov_b64 s[0:1], -1
	s_cbranch_scc0 .LBB0_1263
	s_bitcmp0_b32 s87, 0
	s_cbranch_scc1 .Lro_norm
	v_writelane_b32 v255, 1, 62
	s_mov_b64 s[6:7], exec
	s_load_dwordx2 s[2:3], s[88:89], 0x118
	s_branch .LBB0_1239
